# v102 + the residual-GEMM -> norm XCD barrier (where context-tile workgroups arrive without waiting) gets its own counter word and epoch count, so a workgroup running ahead can no longer be mistaken fo
# baseline (speedup 1.0000x reference)
; #define GLOBAL_PTR(T, p) ((T*)(__attribute__((address_space(1))) T*)(launder_u64((unsigned long long)(p))))
; DI const float* in_ptr(const Args& AR, int i) { asm volatile("" : "+s"(i)); return GLOBAL_PTR(const float, AR.in[i]); }
; #define GRID_SYNC() do { nbar += (unsigned)gridDim.x; grid_barrier(barw, nbar); } while (0)
; __global__ void __launch_bounds__(512, 2) fwd_megakernel(Args args) {
;     ...
;     unsigned* barw = GLOBAL_PTR(unsigned, args.ws); unsigned nbar = 0u;
;     grid.sync();
;     if (PM & 1) prologue_a(F, AR, 5, 6);
;     GRID_SYNC();
;     if (PM & 2) prologue_b(F, AR);
;     GRID_SYNC();
; #pragma unroll 1
;     for (int k_ = 0; k_ < 2; ++k_) {
;         if ((k_ == 0) == ((blockIdx.x & 1) != 0)) norm_phase(F, in_ptr(AR, 0), in_ptr(AR, 2), in_ptr(AR, 4), WSP(float, WS_MOD), 0);
;         else prologue_a(F, AR, 0, 5);
;     }
;     GRID_SYNC();
;     enum { T_NOP = 0, T_NORM, T_SWI, T_RES, T_STORE, T_FT, T_POST, T_SGU, T_ATTE, T_ATTO };
; #pragma unroll 1
;     for (int l = 0; l < 4; ++l) {
.LBB0_183:
	s_or_b64 exec, exec, s[4:5]
	s_add_i32 s2, 0, 0x12000
	v_writelane_b32 v255, s2, 29
	s_add_i32 s2, 0, 0x18810
	s_mov_b64 s[36:37], 0
	s_mov_b32 s21, 0
	s_mov_b32 s96, 0x3e38aa3b
	v_mov_b32_e32 v1, 0
	v_mov_b32_e32 v162, 0x358637bd
	s_mov_b32 s27, 0x800000
	s_mov_b32 s48, 0xf800000
	v_mov_b32_e32 v187, 0x260
	s_mov_b64 s[24:25], 0x80
	v_writelane_b32 v255, s2, 30
	s_movk_i32 s38, 0x1600
	v_mov_b32_e32 v193, 1
	s_barrier
	s_mov_b32 s98, 0
	s_mov_b32 s100, 0
	s_mov_b32 s99, 0
	s_nop 0
	v_writelane_b32 v255, s99, 59
	v_writelane_b32 v255, s99, 60
	v_writelane_b32 v255, s99, 61
	v_writelane_b32 v255, s99, 62
	v_writelane_b32 v255, s99, 63
	s_mov_b32 s101, 0x880f
	s_branch .LBB0_185

; DI void grid_barrier(unsigned* cnt, unsigned target) {
;     asm volatile("s_waitcnt vmcnt(0) lgkmcnt(0)" ::: "memory");
;     __syncthreads();
;     if (threadIdx.x == 0) {
;         __builtin_amdgcn_fence(__ATOMIC_RELEASE, "agent");
;         asm volatile("s_waitcnt vmcnt(0)" ::: "memory");
;         __hip_atomic_fetch_add(cnt, 1u, __ATOMIC_RELAXED, __HIP_MEMORY_SCOPE_AGENT);
;         while (__hip_atomic_load(cnt, __ATOMIC_RELAXED, __HIP_MEMORY_SCOPE_AGENT) < target) __builtin_amdgcn_s_sleep(2);
;         __builtin_amdgcn_fence(__ATOMIC_ACQUIRE, "agent");
;         asm volatile("s_waitcnt vmcnt(0)" ::: "memory");
;     }
;     __syncthreads();
; }
.Lxl_yes:
	s_waitcnt vmcnt(0) lgkmcnt(0)
	s_barrier
	v_readlane_b32 s10, v255, 59
	s_add_u32 s10, s10, 1
	s_nop 0
	v_writelane_b32 v255, s10, 59
	s_lshl_b32 s10, s10, 5
	v_readlane_b32 s2, v255, 0
	s_mov_b64 s[4:5], exec
	v_readlane_b32 s6, v255, 3
	v_readlane_b32 s7, v255, 4
	s_and_b64 s[6:7], s[4:5], s[6:7]
	s_mov_b64 exec, s[6:7]
	s_cbranch_execz .Lxl_done
	s_and_b32 s3, s2, 7
	s_lshl_b32 s3, s3, 2
	s_add_u32 s8, s14, s3
	s_addc_u32 s9, s15, 0
	v_mov_b32_e32 v0, 1
	global_atomic_add v1, v0, s[8:9] offset:96
	s_cmp_lt_u32 s2, 64
	s_cbranch_scc1 .Lxl_done
.Lxl_poll:
	global_load_dword v0, v1, s[8:9] offset:96 sc1
	s_waitcnt vmcnt(0)
	v_cmp_gt_u32_e32 vcc, s10, v0
	s_cbranch_vccz .Lxl_done
	s_sleep 1
	s_branch .Lxl_poll
